# input conversion x to bf16 in the prologue: eight rows per wave with all 32 row loads in flight (was one row ahead)
# baseline (speedup 1.0000x reference)
; DI unsigned pk2(float lo, float hi) { f32x2 v = {lo, hi}; bf16x2_t b = __builtin_convertvector(v, bf16x2_t); return __builtin_bit_cast(unsigned, b); }
; DI u64 ss_to_fix(float ss) { return (u64)(ss * 1048576.f); }
; DI void phase_prologue(int wv, const ArgP a, LAS unsigned char* lds, int parts) {
;     ...
;     const float* x = a.in(0); bf16_t* XB = (bf16_t*)(ws + O_XB) + 2 * 1024; u64* rowss = (u64*)(ws + O_ROWSS);
; #pragma unroll 4
;     for (int t = gw; t < S; t += NGW) {
;         float ss = 0.f;
; #pragma unroll
;         for (int j = 0; j < 4; ++j) { const f32x4 v = __builtin_nontemporal_load((const f32x4*)(x + (size_t)t * 1024 + j * 256 + lane * 4));
;             ss += v[0] * v[0] + v[1] * v[1] + v[2] * v[2] + v[3] * v[3];
;             u32x2 w; w.x = pk2(v[0], v[1]); w.y = pk2(v[2], v[3]); *(u32x2*)(XB + (size_t)t * 1024 + j * 256 + lane * 4) = w; }
;         ss = wave_sum(ss);
;         if (lane == 0) rowss[t] = ss_to_fix(ss);
;         if (lane >= 1 && lane < 5) rowss[(size_t)lane * S + t] = 0ull;
;     }
.LBB0_309:
.Lx8_batch:
	v_mov_b32_e32 v68, v0
	v_mov_b32_e32 v42, v10
	v_mov_b32_e32 v43, v11
	global_load_dwordx4 v[80:83], v[10:11], off offset:-2048 nt
	global_load_dwordx4 v[84:87], v[10:11], off offset:-1024 nt
	global_load_dwordx4 v[88:91], v[10:11], off nt
	global_load_dwordx4 v[92:95], v[10:11], off offset:1024 nt
	v_add_u32_e32 v68, s14, v68
	v_lshl_add_u64 v[42:43], v[42:43], 0, s[16:17]
	v_cmp_lt_i32_e32 vcc, s22, v68
	s_nop 1
	v_cndmask_b32_e32 v40, v42, v10, vcc
	v_cndmask_b32_e32 v41, v43, v11, vcc
	global_load_dwordx4 v[96:99], v[40:41], off offset:-2048 nt
	global_load_dwordx4 v[100:103], v[40:41], off offset:-1024 nt
	global_load_dwordx4 v[104:107], v[40:41], off nt
	global_load_dwordx4 v[108:111], v[40:41], off offset:1024 nt
	v_add_u32_e32 v68, s14, v68
	v_lshl_add_u64 v[42:43], v[42:43], 0, s[16:17]
	v_cmp_lt_i32_e32 vcc, s22, v68
	s_nop 1
	v_cndmask_b32_e32 v40, v42, v10, vcc
	v_cndmask_b32_e32 v41, v43, v11, vcc
	global_load_dwordx4 v[112:115], v[40:41], off offset:-2048 nt
	global_load_dwordx4 v[116:119], v[40:41], off offset:-1024 nt
	global_load_dwordx4 v[120:123], v[40:41], off nt
	global_load_dwordx4 v[124:127], v[40:41], off offset:1024 nt
	v_add_u32_e32 v68, s14, v68
	v_lshl_add_u64 v[42:43], v[42:43], 0, s[16:17]
	v_cmp_lt_i32_e32 vcc, s22, v68
	s_nop 1
	v_cndmask_b32_e32 v40, v42, v10, vcc
	v_cndmask_b32_e32 v41, v43, v11, vcc
	global_load_dwordx4 v[158:161], v[40:41], off offset:-2048 nt
	global_load_dwordx4 v[162:165], v[40:41], off offset:-1024 nt
	global_load_dwordx4 v[166:169], v[40:41], off nt
	global_load_dwordx4 v[170:173], v[40:41], off offset:1024 nt
	v_add_u32_e32 v68, s14, v68
	v_lshl_add_u64 v[42:43], v[42:43], 0, s[16:17]
	v_cmp_lt_i32_e32 vcc, s22, v68
	s_nop 1
	v_cndmask_b32_e32 v40, v42, v10, vcc
	v_cndmask_b32_e32 v41, v43, v11, vcc
	global_load_dwordx4 v[174:177], v[40:41], off offset:-2048 nt
	global_load_dwordx4 v[178:181], v[40:41], off offset:-1024 nt
	global_load_dwordx4 v[182:185], v[40:41], off nt
	global_load_dwordx4 v[186:189], v[40:41], off offset:1024 nt
	v_add_u32_e32 v68, s14, v68
	v_lshl_add_u64 v[42:43], v[42:43], 0, s[16:17]
	v_cmp_lt_i32_e32 vcc, s22, v68
	s_nop 1
	v_cndmask_b32_e32 v40, v42, v10, vcc
	v_cndmask_b32_e32 v41, v43, v11, vcc
	global_load_dwordx4 v[200:203], v[40:41], off offset:-2048 nt
	global_load_dwordx4 v[204:207], v[40:41], off offset:-1024 nt
	global_load_dwordx4 v[208:211], v[40:41], off nt
	global_load_dwordx4 v[212:215], v[40:41], off offset:1024 nt
	v_add_u32_e32 v68, s14, v68
	v_lshl_add_u64 v[42:43], v[42:43], 0, s[16:17]
	v_cmp_lt_i32_e32 vcc, s22, v68
	s_nop 1
	v_cndmask_b32_e32 v40, v42, v10, vcc
	v_cndmask_b32_e32 v41, v43, v11, vcc
	global_load_dwordx4 v[216:219], v[40:41], off offset:-2048 nt
	global_load_dwordx4 v[220:223], v[40:41], off offset:-1024 nt
	global_load_dwordx4 v[224:227], v[40:41], off nt
	global_load_dwordx4 v[228:231], v[40:41], off offset:1024 nt
	v_add_u32_e32 v68, s14, v68
	v_lshl_add_u64 v[42:43], v[42:43], 0, s[16:17]
	v_cmp_lt_i32_e32 vcc, s22, v68
	s_nop 1
	v_cndmask_b32_e32 v40, v42, v10, vcc
	v_cndmask_b32_e32 v41, v43, v11, vcc
	global_load_dwordx4 v[44:47], v[40:41], off offset:-2048 nt
	global_load_dwordx4 v[48:51], v[40:41], off offset:-1024 nt
	global_load_dwordx4 v[52:55], v[40:41], off nt
	global_load_dwordx4 v[56:59], v[40:41], off offset:1024 nt
	v_lshl_add_u64 v[40:41], s[12:13], 0, v[8:9]
	v_add_co_u32_e32 v38, vcc, s15, v40
	s_nop 1
	v_addc_co_u32_e32 v39, vcc, 0, v41, vcc
	s_waitcnt vmcnt(28)
	v_cvt_pk_bf16_f32 v72, v80, v81
	v_cvt_pk_bf16_f32 v73, v82, v83
	global_store_dwordx2 v[38:39], v[72:73], off
	v_mul_f32_e32 v1, v81, v81
	v_fmac_f32_e32 v1, v80, v80
	v_fmac_f32_e32 v1, v82, v82
	v_fmac_f32_e32 v1, v83, v83
	v_cvt_pk_bf16_f32 v74, v84, v85
	v_cvt_pk_bf16_f32 v75, v86, v87
	global_store_dwordx2 v[38:39], v[74:75], off offset:512
	v_mul_f32_e32 v16, v85, v85
	v_fmac_f32_e32 v16, v84, v84
	v_fmac_f32_e32 v16, v86, v86
	v_fmac_f32_e32 v16, v87, v87
	v_add_f32_e32 v1, v1, v16
	v_cvt_pk_bf16_f32 v76, v88, v89
	v_cvt_pk_bf16_f32 v77, v90, v91
	global_store_dwordx2 v[38:39], v[76:77], off offset:1024
	v_mul_f32_e32 v16, v89, v89
	v_fmac_f32_e32 v16, v88, v88
	v_fmac_f32_e32 v16, v90, v90
	v_fmac_f32_e32 v16, v91, v91
	v_add_f32_e32 v1, v1, v16
	v_cvt_pk_bf16_f32 v78, v92, v93
	v_cvt_pk_bf16_f32 v79, v94, v95
	global_store_dwordx2 v[38:39], v[78:79], off offset:1536
	v_mul_f32_e32 v16, v93, v93
	v_fmac_f32_e32 v16, v92, v92
	v_fmac_f32_e32 v16, v94, v94
	v_fmac_f32_e32 v16, v95, v95
	v_add_f32_e32 v1, v1, v16
	ds_bpermute_b32 v16, v12, v1
	s_waitcnt lgkmcnt(0)
	v_add_f32_e32 v1, v1, v16
	ds_bpermute_b32 v16, v13, v1
	s_waitcnt lgkmcnt(0)
	v_add_f32_e32 v1, v1, v16
	ds_bpermute_b32 v16, v17, v1
	s_waitcnt lgkmcnt(0)
	v_add_f32_e32 v1, v1, v16
	ds_bpermute_b32 v16, v18, v1
	s_waitcnt lgkmcnt(0)
	v_add_f32_e32 v1, v1, v16
	ds_bpermute_b32 v16, v19, v1
	s_waitcnt lgkmcnt(0)
	v_add_f32_e32 v1, v1, v16
	ds_bpermute_b32 v16, v20, v1
	s_and_saveexec_b64 s[20:21], s[4:5]
	s_cbranch_execz .Lx8_a0
	s_waitcnt lgkmcnt(0)
	v_add_f32_e32 v1, v1, v16
	v_mul_f32_e32 v1, 0x49800000, v1
	v_trunc_f32_e32 v1, v1
	v_mul_f32_e32 v16, 0x2f800000, v1
	v_floor_f32_e32 v16, v16
	v_fmac_f32_e32 v1, 0xcf800000, v16
	v_cvt_u32_f32_e32 v64, v1
	v_cvt_u32_f32_e32 v65, v16
	v_lshl_add_u64 v[66:67], s[12:13], 0, v[2:3]
	global_store_dwordx2 v[66:67], v[64:65], off

; DI unsigned pk2(float lo, float hi) { f32x2 v = {lo, hi}; bf16x2_t b = __builtin_convertvector(v, bf16x2_t); return __builtin_bit_cast(unsigned, b); }
; DI u64 ss_to_fix(float ss) { return (u64)(ss * 1048576.f); }
; DI void phase_prologue(int wv, const ArgP a, LAS unsigned char* lds, int parts) {
;     ...
;     for (int t = gw; t < S; t += NGW) {
;         float ss = 0.f;
; #pragma unroll
;         for (int j = 0; j < 4; ++j) { const f32x4 v = __builtin_nontemporal_load((const f32x4*)(x + (size_t)t * 1024 + j * 256 + lane * 4));
;             ss += v[0] * v[0] + v[1] * v[1] + v[2] * v[2] + v[3] * v[3];
;             u32x2 w; w.x = pk2(v[0], v[1]); w.y = pk2(v[2], v[3]); *(u32x2*)(XB + (size_t)t * 1024 + j * 256 + lane * 4) = w; }
;         ss = wave_sum(ss);
;         if (lane == 0) rowss[t] = ss_to_fix(ss);
;         if (lane >= 1 && lane < 5) rowss[(size_t)lane * S + t] = 0ull;
;     }
.Lx8_b0:
	s_or_b64 exec, exec, s[20:21]
	v_add_u32_e32 v0, s14, v0
	v_cmp_lt_i32_e32 vcc, s22, v0
	v_lshl_add_u64 v[2:3], v[2:3], 0, s[8:9]
	v_lshl_add_u64 v[6:7], v[6:7], 0, s[8:9]
	v_lshl_add_u64 v[8:9], v[8:9], 0, s[10:11]
	s_or_b64 s[18:19], vcc, s[18:19]
	v_lshl_add_u64 v[10:11], v[10:11], 0, s[16:17]
	s_andn2_b64 exec, exec, s[18:19]
	s_cbranch_execz .Lxc_exit
	v_lshl_add_u64 v[40:41], s[12:13], 0, v[8:9]
	v_add_co_u32_e32 v38, vcc, s15, v40
	s_nop 1
	v_addc_co_u32_e32 v39, vcc, 0, v41, vcc
	s_waitcnt vmcnt(24)
	v_cvt_pk_bf16_f32 v72, v96, v97
	v_cvt_pk_bf16_f32 v73, v98, v99
	global_store_dwordx2 v[38:39], v[72:73], off
	v_mul_f32_e32 v1, v97, v97
	v_fmac_f32_e32 v1, v96, v96
	v_fmac_f32_e32 v1, v98, v98
	v_fmac_f32_e32 v1, v99, v99
	v_cvt_pk_bf16_f32 v74, v100, v101
	v_cvt_pk_bf16_f32 v75, v102, v103
	global_store_dwordx2 v[38:39], v[74:75], off offset:512
	v_mul_f32_e32 v16, v101, v101
	v_fmac_f32_e32 v16, v100, v100
	v_fmac_f32_e32 v16, v102, v102
	v_fmac_f32_e32 v16, v103, v103
	v_add_f32_e32 v1, v1, v16
	v_cvt_pk_bf16_f32 v76, v104, v105
	v_cvt_pk_bf16_f32 v77, v106, v107
	global_store_dwordx2 v[38:39], v[76:77], off offset:1024
	v_mul_f32_e32 v16, v105, v105
	v_fmac_f32_e32 v16, v104, v104
	v_fmac_f32_e32 v16, v106, v106
	v_fmac_f32_e32 v16, v107, v107
	v_add_f32_e32 v1, v1, v16
	v_cvt_pk_bf16_f32 v78, v108, v109
	v_cvt_pk_bf16_f32 v79, v110, v111
	global_store_dwordx2 v[38:39], v[78:79], off offset:1536
	v_mul_f32_e32 v16, v109, v109
	v_fmac_f32_e32 v16, v108, v108
	v_fmac_f32_e32 v16, v110, v110
	v_fmac_f32_e32 v16, v111, v111
	v_add_f32_e32 v1, v1, v16
	ds_bpermute_b32 v16, v12, v1
	s_waitcnt lgkmcnt(0)
	v_add_f32_e32 v1, v1, v16
	ds_bpermute_b32 v16, v13, v1
	s_waitcnt lgkmcnt(0)
	v_add_f32_e32 v1, v1, v16
	ds_bpermute_b32 v16, v17, v1
	s_waitcnt lgkmcnt(0)
	v_add_f32_e32 v1, v1, v16
	ds_bpermute_b32 v16, v18, v1
	s_waitcnt lgkmcnt(0)
	v_add_f32_e32 v1, v1, v16
	ds_bpermute_b32 v16, v19, v1
	s_waitcnt lgkmcnt(0)
	v_add_f32_e32 v1, v1, v16
	ds_bpermute_b32 v16, v20, v1
	s_and_saveexec_b64 s[20:21], s[4:5]
	s_cbranch_execz .Lx8_a1
	s_waitcnt lgkmcnt(0)
	v_add_f32_e32 v1, v1, v16
	v_mul_f32_e32 v1, 0x49800000, v1
	v_trunc_f32_e32 v1, v1
	v_mul_f32_e32 v16, 0x2f800000, v1
	v_floor_f32_e32 v16, v16
	v_fmac_f32_e32 v1, 0xcf800000, v16
	v_cvt_u32_f32_e32 v64, v1
	v_cvt_u32_f32_e32 v65, v16
	v_lshl_add_u64 v[66:67], s[12:13], 0, v[2:3]
	global_store_dwordx2 v[66:67], v[64:65], off

; DI unsigned pk2(float lo, float hi) { f32x2 v = {lo, hi}; bf16x2_t b = __builtin_convertvector(v, bf16x2_t); return __builtin_bit_cast(unsigned, b); }
; DI u64 ss_to_fix(float ss) { return (u64)(ss * 1048576.f); }
; DI void phase_prologue(int wv, const ArgP a, LAS unsigned char* lds, int parts) {
;     ...
;     for (int t = gw; t < S; t += NGW) {
;         float ss = 0.f;
; #pragma unroll
;         for (int j = 0; j < 4; ++j) { const f32x4 v = __builtin_nontemporal_load((const f32x4*)(x + (size_t)t * 1024 + j * 256 + lane * 4));
;             ss += v[0] * v[0] + v[1] * v[1] + v[2] * v[2] + v[3] * v[3];
;             u32x2 w; w.x = pk2(v[0], v[1]); w.y = pk2(v[2], v[3]); *(u32x2*)(XB + (size_t)t * 1024 + j * 256 + lane * 4) = w; }
;         ss = wave_sum(ss);
;         if (lane == 0) rowss[t] = ss_to_fix(ss);
;         if (lane >= 1 && lane < 5) rowss[(size_t)lane * S + t] = 0ull;
;     }
.Lx8_b1:
	s_or_b64 exec, exec, s[20:21]
	v_add_u32_e32 v0, s14, v0
	v_cmp_lt_i32_e32 vcc, s22, v0
	v_lshl_add_u64 v[2:3], v[2:3], 0, s[8:9]
	v_lshl_add_u64 v[6:7], v[6:7], 0, s[8:9]
	v_lshl_add_u64 v[8:9], v[8:9], 0, s[10:11]
	s_or_b64 s[18:19], vcc, s[18:19]
	v_lshl_add_u64 v[10:11], v[10:11], 0, s[16:17]
	s_andn2_b64 exec, exec, s[18:19]
	s_cbranch_execz .Lxc_exit
	v_lshl_add_u64 v[40:41], s[12:13], 0, v[8:9]
	v_add_co_u32_e32 v38, vcc, s15, v40
	s_nop 1
	v_addc_co_u32_e32 v39, vcc, 0, v41, vcc
	s_waitcnt vmcnt(20)
	v_cvt_pk_bf16_f32 v72, v112, v113
	v_cvt_pk_bf16_f32 v73, v114, v115
	global_store_dwordx2 v[38:39], v[72:73], off
	v_mul_f32_e32 v1, v113, v113
	v_fmac_f32_e32 v1, v112, v112
	v_fmac_f32_e32 v1, v114, v114
	v_fmac_f32_e32 v1, v115, v115
	v_cvt_pk_bf16_f32 v74, v116, v117
	v_cvt_pk_bf16_f32 v75, v118, v119
	global_store_dwordx2 v[38:39], v[74:75], off offset:512
	v_mul_f32_e32 v16, v117, v117
	v_fmac_f32_e32 v16, v116, v116
	v_fmac_f32_e32 v16, v118, v118
	v_fmac_f32_e32 v16, v119, v119
	v_add_f32_e32 v1, v1, v16
	v_cvt_pk_bf16_f32 v76, v120, v121
	v_cvt_pk_bf16_f32 v77, v122, v123
	global_store_dwordx2 v[38:39], v[76:77], off offset:1024
	v_mul_f32_e32 v16, v121, v121
	v_fmac_f32_e32 v16, v120, v120
	v_fmac_f32_e32 v16, v122, v122
	v_fmac_f32_e32 v16, v123, v123
	v_add_f32_e32 v1, v1, v16
	v_cvt_pk_bf16_f32 v78, v124, v125
	v_cvt_pk_bf16_f32 v79, v126, v127
	global_store_dwordx2 v[38:39], v[78:79], off offset:1536
	v_mul_f32_e32 v16, v125, v125
	v_fmac_f32_e32 v16, v124, v124
	v_fmac_f32_e32 v16, v126, v126
	v_fmac_f32_e32 v16, v127, v127
	v_add_f32_e32 v1, v1, v16
	ds_bpermute_b32 v16, v12, v1
	s_waitcnt lgkmcnt(0)
	v_add_f32_e32 v1, v1, v16
	ds_bpermute_b32 v16, v13, v1
	s_waitcnt lgkmcnt(0)
	v_add_f32_e32 v1, v1, v16
	ds_bpermute_b32 v16, v17, v1
	s_waitcnt lgkmcnt(0)
	v_add_f32_e32 v1, v1, v16
	ds_bpermute_b32 v16, v18, v1
	s_waitcnt lgkmcnt(0)
	v_add_f32_e32 v1, v1, v16
	ds_bpermute_b32 v16, v19, v1
	s_waitcnt lgkmcnt(0)
	v_add_f32_e32 v1, v1, v16
	ds_bpermute_b32 v16, v20, v1
	s_and_saveexec_b64 s[20:21], s[4:5]
	s_cbranch_execz .Lx8_a2
	s_waitcnt lgkmcnt(0)
	v_add_f32_e32 v1, v1, v16
	v_mul_f32_e32 v1, 0x49800000, v1
	v_trunc_f32_e32 v1, v1
	v_mul_f32_e32 v16, 0x2f800000, v1
	v_floor_f32_e32 v16, v16
	v_fmac_f32_e32 v1, 0xcf800000, v16
	v_cvt_u32_f32_e32 v64, v1
	v_cvt_u32_f32_e32 v65, v16
	v_lshl_add_u64 v[66:67], s[12:13], 0, v[2:3]
	global_store_dwordx2 v[66:67], v[64:65], off

; DI unsigned pk2(float lo, float hi) { f32x2 v = {lo, hi}; bf16x2_t b = __builtin_convertvector(v, bf16x2_t); return __builtin_bit_cast(unsigned, b); }
; DI u64 ss_to_fix(float ss) { return (u64)(ss * 1048576.f); }
; DI void phase_prologue(int wv, const ArgP a, LAS unsigned char* lds, int parts) {
;     ...
;     for (int t = gw; t < S; t += NGW) {
;         float ss = 0.f;
; #pragma unroll
;         for (int j = 0; j < 4; ++j) { const f32x4 v = __builtin_nontemporal_load((const f32x4*)(x + (size_t)t * 1024 + j * 256 + lane * 4));
;             ss += v[0] * v[0] + v[1] * v[1] + v[2] * v[2] + v[3] * v[3];
;             u32x2 w; w.x = pk2(v[0], v[1]); w.y = pk2(v[2], v[3]); *(u32x2*)(XB + (size_t)t * 1024 + j * 256 + lane * 4) = w; }
;         ss = wave_sum(ss);
;         if (lane == 0) rowss[t] = ss_to_fix(ss);
;         if (lane >= 1 && lane < 5) rowss[(size_t)lane * S + t] = 0ull;
;     }
.Lx8_b2:
	s_or_b64 exec, exec, s[20:21]
	v_add_u32_e32 v0, s14, v0
	v_cmp_lt_i32_e32 vcc, s22, v0
	v_lshl_add_u64 v[2:3], v[2:3], 0, s[8:9]
	v_lshl_add_u64 v[6:7], v[6:7], 0, s[8:9]
	v_lshl_add_u64 v[8:9], v[8:9], 0, s[10:11]
	s_or_b64 s[18:19], vcc, s[18:19]
	v_lshl_add_u64 v[10:11], v[10:11], 0, s[16:17]
	s_andn2_b64 exec, exec, s[18:19]
	s_cbranch_execz .Lxc_exit
	v_lshl_add_u64 v[40:41], s[12:13], 0, v[8:9]
	v_add_co_u32_e32 v38, vcc, s15, v40
	s_nop 1
	v_addc_co_u32_e32 v39, vcc, 0, v41, vcc
	s_waitcnt vmcnt(16)
	v_cvt_pk_bf16_f32 v72, v158, v159
	v_cvt_pk_bf16_f32 v73, v160, v161
	global_store_dwordx2 v[38:39], v[72:73], off
	v_mul_f32_e32 v1, v159, v159
	v_fmac_f32_e32 v1, v158, v158
	v_fmac_f32_e32 v1, v160, v160
	v_fmac_f32_e32 v1, v161, v161
	v_cvt_pk_bf16_f32 v74, v162, v163
	v_cvt_pk_bf16_f32 v75, v164, v165
	global_store_dwordx2 v[38:39], v[74:75], off offset:512
	v_mul_f32_e32 v16, v163, v163
	v_fmac_f32_e32 v16, v162, v162
	v_fmac_f32_e32 v16, v164, v164
	v_fmac_f32_e32 v16, v165, v165
	v_add_f32_e32 v1, v1, v16
	v_cvt_pk_bf16_f32 v76, v166, v167
	v_cvt_pk_bf16_f32 v77, v168, v169
	global_store_dwordx2 v[38:39], v[76:77], off offset:1024
	v_mul_f32_e32 v16, v167, v167
	v_fmac_f32_e32 v16, v166, v166
	v_fmac_f32_e32 v16, v168, v168
	v_fmac_f32_e32 v16, v169, v169
	v_add_f32_e32 v1, v1, v16
	v_cvt_pk_bf16_f32 v78, v170, v171
	v_cvt_pk_bf16_f32 v79, v172, v173
	global_store_dwordx2 v[38:39], v[78:79], off offset:1536
	v_mul_f32_e32 v16, v171, v171
	v_fmac_f32_e32 v16, v170, v170
	v_fmac_f32_e32 v16, v172, v172
	v_fmac_f32_e32 v16, v173, v173
	v_add_f32_e32 v1, v1, v16
	ds_bpermute_b32 v16, v12, v1
	s_waitcnt lgkmcnt(0)
	v_add_f32_e32 v1, v1, v16
	ds_bpermute_b32 v16, v13, v1
	s_waitcnt lgkmcnt(0)
	v_add_f32_e32 v1, v1, v16
	ds_bpermute_b32 v16, v17, v1
	s_waitcnt lgkmcnt(0)
	v_add_f32_e32 v1, v1, v16
	ds_bpermute_b32 v16, v18, v1
	s_waitcnt lgkmcnt(0)
	v_add_f32_e32 v1, v1, v16
	ds_bpermute_b32 v16, v19, v1
	s_waitcnt lgkmcnt(0)
	v_add_f32_e32 v1, v1, v16
	ds_bpermute_b32 v16, v20, v1
	s_and_saveexec_b64 s[20:21], s[4:5]
	s_cbranch_execz .Lx8_a3
	s_waitcnt lgkmcnt(0)
	v_add_f32_e32 v1, v1, v16
	v_mul_f32_e32 v1, 0x49800000, v1
	v_trunc_f32_e32 v1, v1
	v_mul_f32_e32 v16, 0x2f800000, v1
	v_floor_f32_e32 v16, v16
	v_fmac_f32_e32 v1, 0xcf800000, v16
	v_cvt_u32_f32_e32 v64, v1
	v_cvt_u32_f32_e32 v65, v16
	v_lshl_add_u64 v[66:67], s[12:13], 0, v[2:3]
	global_store_dwordx2 v[66:67], v[64:65], off

; DI unsigned pk2(float lo, float hi) { f32x2 v = {lo, hi}; bf16x2_t b = __builtin_convertvector(v, bf16x2_t); return __builtin_bit_cast(unsigned, b); }
; DI u64 ss_to_fix(float ss) { return (u64)(ss * 1048576.f); }
; DI void phase_prologue(int wv, const ArgP a, LAS unsigned char* lds, int parts) {
;     ...
;     for (int t = gw; t < S; t += NGW) {
;         float ss = 0.f;
; #pragma unroll
;         for (int j = 0; j < 4; ++j) { const f32x4 v = __builtin_nontemporal_load((const f32x4*)(x + (size_t)t * 1024 + j * 256 + lane * 4));
;             ss += v[0] * v[0] + v[1] * v[1] + v[2] * v[2] + v[3] * v[3];
;             u32x2 w; w.x = pk2(v[0], v[1]); w.y = pk2(v[2], v[3]); *(u32x2*)(XB + (size_t)t * 1024 + j * 256 + lane * 4) = w; }
;         ss = wave_sum(ss);
;         if (lane == 0) rowss[t] = ss_to_fix(ss);
;         if (lane >= 1 && lane < 5) rowss[(size_t)lane * S + t] = 0ull;
;     }
.Lx8_b3:
	s_or_b64 exec, exec, s[20:21]
	v_add_u32_e32 v0, s14, v0
	v_cmp_lt_i32_e32 vcc, s22, v0
	v_lshl_add_u64 v[2:3], v[2:3], 0, s[8:9]
	v_lshl_add_u64 v[6:7], v[6:7], 0, s[8:9]
	v_lshl_add_u64 v[8:9], v[8:9], 0, s[10:11]
	s_or_b64 s[18:19], vcc, s[18:19]
	v_lshl_add_u64 v[10:11], v[10:11], 0, s[16:17]
	s_andn2_b64 exec, exec, s[18:19]
	s_cbranch_execz .Lxc_exit
	v_lshl_add_u64 v[40:41], s[12:13], 0, v[8:9]
	v_add_co_u32_e32 v38, vcc, s15, v40
	s_nop 1
	v_addc_co_u32_e32 v39, vcc, 0, v41, vcc
	s_waitcnt vmcnt(12)
	v_cvt_pk_bf16_f32 v72, v174, v175
	v_cvt_pk_bf16_f32 v73, v176, v177
	global_store_dwordx2 v[38:39], v[72:73], off
	v_mul_f32_e32 v1, v175, v175
	v_fmac_f32_e32 v1, v174, v174
	v_fmac_f32_e32 v1, v176, v176
	v_fmac_f32_e32 v1, v177, v177
	v_cvt_pk_bf16_f32 v74, v178, v179
	v_cvt_pk_bf16_f32 v75, v180, v181
	global_store_dwordx2 v[38:39], v[74:75], off offset:512
	v_mul_f32_e32 v16, v179, v179
	v_fmac_f32_e32 v16, v178, v178
	v_fmac_f32_e32 v16, v180, v180
	v_fmac_f32_e32 v16, v181, v181
	v_add_f32_e32 v1, v1, v16
	v_cvt_pk_bf16_f32 v76, v182, v183
	v_cvt_pk_bf16_f32 v77, v184, v185
	global_store_dwordx2 v[38:39], v[76:77], off offset:1024
	v_mul_f32_e32 v16, v183, v183
	v_fmac_f32_e32 v16, v182, v182
	v_fmac_f32_e32 v16, v184, v184
	v_fmac_f32_e32 v16, v185, v185
	v_add_f32_e32 v1, v1, v16
	v_cvt_pk_bf16_f32 v78, v186, v187
	v_cvt_pk_bf16_f32 v79, v188, v189
	global_store_dwordx2 v[38:39], v[78:79], off offset:1536
	v_mul_f32_e32 v16, v187, v187
	v_fmac_f32_e32 v16, v186, v186
	v_fmac_f32_e32 v16, v188, v188
	v_fmac_f32_e32 v16, v189, v189
	v_add_f32_e32 v1, v1, v16
	ds_bpermute_b32 v16, v12, v1
	s_waitcnt lgkmcnt(0)
	v_add_f32_e32 v1, v1, v16
	ds_bpermute_b32 v16, v13, v1
	s_waitcnt lgkmcnt(0)
	v_add_f32_e32 v1, v1, v16
	ds_bpermute_b32 v16, v17, v1
	s_waitcnt lgkmcnt(0)
	v_add_f32_e32 v1, v1, v16
	ds_bpermute_b32 v16, v18, v1
	s_waitcnt lgkmcnt(0)
	v_add_f32_e32 v1, v1, v16
	ds_bpermute_b32 v16, v19, v1
	s_waitcnt lgkmcnt(0)
	v_add_f32_e32 v1, v1, v16
	ds_bpermute_b32 v16, v20, v1
	s_and_saveexec_b64 s[20:21], s[4:5]
	s_cbranch_execz .Lx8_a4
	s_waitcnt lgkmcnt(0)
	v_add_f32_e32 v1, v1, v16
	v_mul_f32_e32 v1, 0x49800000, v1
	v_trunc_f32_e32 v1, v1
	v_mul_f32_e32 v16, 0x2f800000, v1
	v_floor_f32_e32 v16, v16
	v_fmac_f32_e32 v1, 0xcf800000, v16
	v_cvt_u32_f32_e32 v64, v1
	v_cvt_u32_f32_e32 v65, v16
	v_lshl_add_u64 v[66:67], s[12:13], 0, v[2:3]
	global_store_dwordx2 v[66:67], v[64:65], off

; DI unsigned pk2(float lo, float hi) { f32x2 v = {lo, hi}; bf16x2_t b = __builtin_convertvector(v, bf16x2_t); return __builtin_bit_cast(unsigned, b); }
; DI u64 ss_to_fix(float ss) { return (u64)(ss * 1048576.f); }
; DI void phase_prologue(int wv, const ArgP a, LAS unsigned char* lds, int parts) {
;     ...
;     for (int t = gw; t < S; t += NGW) {
;         float ss = 0.f;
; #pragma unroll
;         for (int j = 0; j < 4; ++j) { const f32x4 v = __builtin_nontemporal_load((const f32x4*)(x + (size_t)t * 1024 + j * 256 + lane * 4));
;             ss += v[0] * v[0] + v[1] * v[1] + v[2] * v[2] + v[3] * v[3];
;             u32x2 w; w.x = pk2(v[0], v[1]); w.y = pk2(v[2], v[3]); *(u32x2*)(XB + (size_t)t * 1024 + j * 256 + lane * 4) = w; }
;         ss = wave_sum(ss);
;         if (lane == 0) rowss[t] = ss_to_fix(ss);
;         if (lane >= 1 && lane < 5) rowss[(size_t)lane * S + t] = 0ull;
;     }
.Lx8_b4:
	s_or_b64 exec, exec, s[20:21]
	v_add_u32_e32 v0, s14, v0
	v_cmp_lt_i32_e32 vcc, s22, v0
	v_lshl_add_u64 v[2:3], v[2:3], 0, s[8:9]
	v_lshl_add_u64 v[6:7], v[6:7], 0, s[8:9]
	v_lshl_add_u64 v[8:9], v[8:9], 0, s[10:11]
	s_or_b64 s[18:19], vcc, s[18:19]
	v_lshl_add_u64 v[10:11], v[10:11], 0, s[16:17]
	s_andn2_b64 exec, exec, s[18:19]
	s_cbranch_execz .Lxc_exit
	v_lshl_add_u64 v[40:41], s[12:13], 0, v[8:9]
	v_add_co_u32_e32 v38, vcc, s15, v40
	s_nop 1
	v_addc_co_u32_e32 v39, vcc, 0, v41, vcc
	s_waitcnt vmcnt(8)
	v_cvt_pk_bf16_f32 v72, v200, v201
	v_cvt_pk_bf16_f32 v73, v202, v203
	global_store_dwordx2 v[38:39], v[72:73], off
	v_mul_f32_e32 v1, v201, v201
	v_fmac_f32_e32 v1, v200, v200
	v_fmac_f32_e32 v1, v202, v202
	v_fmac_f32_e32 v1, v203, v203
	v_cvt_pk_bf16_f32 v74, v204, v205
	v_cvt_pk_bf16_f32 v75, v206, v207
	global_store_dwordx2 v[38:39], v[74:75], off offset:512
	v_mul_f32_e32 v16, v205, v205
	v_fmac_f32_e32 v16, v204, v204
	v_fmac_f32_e32 v16, v206, v206
	v_fmac_f32_e32 v16, v207, v207
	v_add_f32_e32 v1, v1, v16
	v_cvt_pk_bf16_f32 v76, v208, v209
	v_cvt_pk_bf16_f32 v77, v210, v211
	global_store_dwordx2 v[38:39], v[76:77], off offset:1024
	v_mul_f32_e32 v16, v209, v209
	v_fmac_f32_e32 v16, v208, v208
	v_fmac_f32_e32 v16, v210, v210
	v_fmac_f32_e32 v16, v211, v211
	v_add_f32_e32 v1, v1, v16
	v_cvt_pk_bf16_f32 v78, v212, v213
	v_cvt_pk_bf16_f32 v79, v214, v215
	global_store_dwordx2 v[38:39], v[78:79], off offset:1536
	v_mul_f32_e32 v16, v213, v213
	v_fmac_f32_e32 v16, v212, v212
	v_fmac_f32_e32 v16, v214, v214
	v_fmac_f32_e32 v16, v215, v215
	v_add_f32_e32 v1, v1, v16
	ds_bpermute_b32 v16, v12, v1
	s_waitcnt lgkmcnt(0)
	v_add_f32_e32 v1, v1, v16
	ds_bpermute_b32 v16, v13, v1
	s_waitcnt lgkmcnt(0)
	v_add_f32_e32 v1, v1, v16
	ds_bpermute_b32 v16, v17, v1
	s_waitcnt lgkmcnt(0)
	v_add_f32_e32 v1, v1, v16
	ds_bpermute_b32 v16, v18, v1
	s_waitcnt lgkmcnt(0)
	v_add_f32_e32 v1, v1, v16
	ds_bpermute_b32 v16, v19, v1
	s_waitcnt lgkmcnt(0)
	v_add_f32_e32 v1, v1, v16
	ds_bpermute_b32 v16, v20, v1
	s_and_saveexec_b64 s[20:21], s[4:5]
	s_cbranch_execz .Lx8_a5
	s_waitcnt lgkmcnt(0)
	v_add_f32_e32 v1, v1, v16
	v_mul_f32_e32 v1, 0x49800000, v1
	v_trunc_f32_e32 v1, v1
	v_mul_f32_e32 v16, 0x2f800000, v1
	v_floor_f32_e32 v16, v16
	v_fmac_f32_e32 v1, 0xcf800000, v16
	v_cvt_u32_f32_e32 v64, v1
	v_cvt_u32_f32_e32 v65, v16
	v_lshl_add_u64 v[66:67], s[12:13], 0, v[2:3]
	global_store_dwordx2 v[66:67], v[64:65], off

; DI unsigned pk2(float lo, float hi) { f32x2 v = {lo, hi}; bf16x2_t b = __builtin_convertvector(v, bf16x2_t); return __builtin_bit_cast(unsigned, b); }
; DI u64 ss_to_fix(float ss) { return (u64)(ss * 1048576.f); }
; DI void phase_prologue(int wv, const ArgP a, LAS unsigned char* lds, int parts) {
;     ...
;     for (int t = gw; t < S; t += NGW) {
;         float ss = 0.f;
; #pragma unroll
;         for (int j = 0; j < 4; ++j) { const f32x4 v = __builtin_nontemporal_load((const f32x4*)(x + (size_t)t * 1024 + j * 256 + lane * 4));
;             ss += v[0] * v[0] + v[1] * v[1] + v[2] * v[2] + v[3] * v[3];
;             u32x2 w; w.x = pk2(v[0], v[1]); w.y = pk2(v[2], v[3]); *(u32x2*)(XB + (size_t)t * 1024 + j * 256 + lane * 4) = w; }
;         ss = wave_sum(ss);
;         if (lane == 0) rowss[t] = ss_to_fix(ss);
;         if (lane >= 1 && lane < 5) rowss[(size_t)lane * S + t] = 0ull;
;     }
.Lx8_b5:
	s_or_b64 exec, exec, s[20:21]
	v_add_u32_e32 v0, s14, v0
	v_cmp_lt_i32_e32 vcc, s22, v0
	v_lshl_add_u64 v[2:3], v[2:3], 0, s[8:9]
	v_lshl_add_u64 v[6:7], v[6:7], 0, s[8:9]
	v_lshl_add_u64 v[8:9], v[8:9], 0, s[10:11]
	s_or_b64 s[18:19], vcc, s[18:19]
	v_lshl_add_u64 v[10:11], v[10:11], 0, s[16:17]
	s_andn2_b64 exec, exec, s[18:19]
	s_cbranch_execz .Lxc_exit
	v_lshl_add_u64 v[40:41], s[12:13], 0, v[8:9]
	v_add_co_u32_e32 v38, vcc, s15, v40
	s_nop 1
	v_addc_co_u32_e32 v39, vcc, 0, v41, vcc
	s_waitcnt vmcnt(4)
	v_cvt_pk_bf16_f32 v72, v216, v217
	v_cvt_pk_bf16_f32 v73, v218, v219
	global_store_dwordx2 v[38:39], v[72:73], off
	v_mul_f32_e32 v1, v217, v217
	v_fmac_f32_e32 v1, v216, v216
	v_fmac_f32_e32 v1, v218, v218
	v_fmac_f32_e32 v1, v219, v219
	v_cvt_pk_bf16_f32 v74, v220, v221
	v_cvt_pk_bf16_f32 v75, v222, v223
	global_store_dwordx2 v[38:39], v[74:75], off offset:512
	v_mul_f32_e32 v16, v221, v221
	v_fmac_f32_e32 v16, v220, v220
	v_fmac_f32_e32 v16, v222, v222
	v_fmac_f32_e32 v16, v223, v223
	v_add_f32_e32 v1, v1, v16
	v_cvt_pk_bf16_f32 v76, v224, v225
	v_cvt_pk_bf16_f32 v77, v226, v227
	global_store_dwordx2 v[38:39], v[76:77], off offset:1024
	v_mul_f32_e32 v16, v225, v225
	v_fmac_f32_e32 v16, v224, v224
	v_fmac_f32_e32 v16, v226, v226
	v_fmac_f32_e32 v16, v227, v227
	v_add_f32_e32 v1, v1, v16
	v_cvt_pk_bf16_f32 v78, v228, v229
	v_cvt_pk_bf16_f32 v79, v230, v231
	global_store_dwordx2 v[38:39], v[78:79], off offset:1536
	v_mul_f32_e32 v16, v229, v229
	v_fmac_f32_e32 v16, v228, v228
	v_fmac_f32_e32 v16, v230, v230
	v_fmac_f32_e32 v16, v231, v231
	v_add_f32_e32 v1, v1, v16
	ds_bpermute_b32 v16, v12, v1
	s_waitcnt lgkmcnt(0)
	v_add_f32_e32 v1, v1, v16
	ds_bpermute_b32 v16, v13, v1
	s_waitcnt lgkmcnt(0)
	v_add_f32_e32 v1, v1, v16
	ds_bpermute_b32 v16, v17, v1
	s_waitcnt lgkmcnt(0)
	v_add_f32_e32 v1, v1, v16
	ds_bpermute_b32 v16, v18, v1
	s_waitcnt lgkmcnt(0)
	v_add_f32_e32 v1, v1, v16
	ds_bpermute_b32 v16, v19, v1
	s_waitcnt lgkmcnt(0)
	v_add_f32_e32 v1, v1, v16
	ds_bpermute_b32 v16, v20, v1
	s_and_saveexec_b64 s[20:21], s[4:5]
	s_cbranch_execz .Lx8_a6
	s_waitcnt lgkmcnt(0)
	v_add_f32_e32 v1, v1, v16
	v_mul_f32_e32 v1, 0x49800000, v1
	v_trunc_f32_e32 v1, v1
	v_mul_f32_e32 v16, 0x2f800000, v1
	v_floor_f32_e32 v16, v16
	v_fmac_f32_e32 v1, 0xcf800000, v16
	v_cvt_u32_f32_e32 v64, v1
	v_cvt_u32_f32_e32 v65, v16
	v_lshl_add_u64 v[66:67], s[12:13], 0, v[2:3]
	global_store_dwordx2 v[66:67], v[64:65], off

; DI unsigned pk2(float lo, float hi) { f32x2 v = {lo, hi}; bf16x2_t b = __builtin_convertvector(v, bf16x2_t); return __builtin_bit_cast(unsigned, b); }
; DI u64 ss_to_fix(float ss) { return (u64)(ss * 1048576.f); }
; DI void phase_prologue(int wv, const ArgP a, LAS unsigned char* lds, int parts) {
;     ...
;     for (int t = gw; t < S; t += NGW) {
;         float ss = 0.f;
; #pragma unroll
;         for (int j = 0; j < 4; ++j) { const f32x4 v = __builtin_nontemporal_load((const f32x4*)(x + (size_t)t * 1024 + j * 256 + lane * 4));
;             ss += v[0] * v[0] + v[1] * v[1] + v[2] * v[2] + v[3] * v[3];
;             u32x2 w; w.x = pk2(v[0], v[1]); w.y = pk2(v[2], v[3]); *(u32x2*)(XB + (size_t)t * 1024 + j * 256 + lane * 4) = w; }
;         ss = wave_sum(ss);
;         if (lane == 0) rowss[t] = ss_to_fix(ss);
;         if (lane >= 1 && lane < 5) rowss[(size_t)lane * S + t] = 0ull;
;     }
.Lx8_b6:
	s_or_b64 exec, exec, s[20:21]
	v_add_u32_e32 v0, s14, v0
	v_cmp_lt_i32_e32 vcc, s22, v0
	v_lshl_add_u64 v[2:3], v[2:3], 0, s[8:9]
	v_lshl_add_u64 v[6:7], v[6:7], 0, s[8:9]
	v_lshl_add_u64 v[8:9], v[8:9], 0, s[10:11]
	s_or_b64 s[18:19], vcc, s[18:19]
	v_lshl_add_u64 v[10:11], v[10:11], 0, s[16:17]
	s_andn2_b64 exec, exec, s[18:19]
	s_cbranch_execz .Lxc_exit
	v_lshl_add_u64 v[40:41], s[12:13], 0, v[8:9]
	v_add_co_u32_e32 v38, vcc, s15, v40
	s_nop 1
	v_addc_co_u32_e32 v39, vcc, 0, v41, vcc
	s_waitcnt vmcnt(0)
	v_cvt_pk_bf16_f32 v72, v44, v45
	v_cvt_pk_bf16_f32 v73, v46, v47
	global_store_dwordx2 v[38:39], v[72:73], off
	v_mul_f32_e32 v1, v45, v45
	v_fmac_f32_e32 v1, v44, v44
	v_fmac_f32_e32 v1, v46, v46
	v_fmac_f32_e32 v1, v47, v47
	v_cvt_pk_bf16_f32 v74, v48, v49
	v_cvt_pk_bf16_f32 v75, v50, v51
	global_store_dwordx2 v[38:39], v[74:75], off offset:512
	v_mul_f32_e32 v16, v49, v49
	v_fmac_f32_e32 v16, v48, v48
	v_fmac_f32_e32 v16, v50, v50
	v_fmac_f32_e32 v16, v51, v51
	v_add_f32_e32 v1, v1, v16
	v_cvt_pk_bf16_f32 v76, v52, v53
	v_cvt_pk_bf16_f32 v77, v54, v55
	global_store_dwordx2 v[38:39], v[76:77], off offset:1024
	v_mul_f32_e32 v16, v53, v53
	v_fmac_f32_e32 v16, v52, v52
	v_fmac_f32_e32 v16, v54, v54
	v_fmac_f32_e32 v16, v55, v55
	v_add_f32_e32 v1, v1, v16
	v_cvt_pk_bf16_f32 v78, v56, v57
	v_cvt_pk_bf16_f32 v79, v58, v59
	global_store_dwordx2 v[38:39], v[78:79], off offset:1536
	v_mul_f32_e32 v16, v57, v57
	v_fmac_f32_e32 v16, v56, v56
	v_fmac_f32_e32 v16, v58, v58
	v_fmac_f32_e32 v16, v59, v59
	v_add_f32_e32 v1, v1, v16
	ds_bpermute_b32 v16, v12, v1
	s_waitcnt lgkmcnt(0)
	v_add_f32_e32 v1, v1, v16
	ds_bpermute_b32 v16, v13, v1
	s_waitcnt lgkmcnt(0)
	v_add_f32_e32 v1, v1, v16
	ds_bpermute_b32 v16, v17, v1
	s_waitcnt lgkmcnt(0)
	v_add_f32_e32 v1, v1, v16
	ds_bpermute_b32 v16, v18, v1
	s_waitcnt lgkmcnt(0)
	v_add_f32_e32 v1, v1, v16
	ds_bpermute_b32 v16, v19, v1
	s_waitcnt lgkmcnt(0)
	v_add_f32_e32 v1, v1, v16
	ds_bpermute_b32 v16, v20, v1
	s_and_saveexec_b64 s[20:21], s[4:5]
	s_cbranch_execz .Lx8_a7
	s_waitcnt lgkmcnt(0)
	v_add_f32_e32 v1, v1, v16
	v_mul_f32_e32 v1, 0x49800000, v1
	v_trunc_f32_e32 v1, v1
	v_mul_f32_e32 v16, 0x2f800000, v1
	v_floor_f32_e32 v16, v16
	v_fmac_f32_e32 v1, 0xcf800000, v16
	v_cvt_u32_f32_e32 v64, v1
	v_cvt_u32_f32_e32 v65, v16
	v_lshl_add_u64 v[66:67], s[12:13], 0, v[2:3]
	global_store_dwordx2 v[66:67], v[64:65], off
